# rsl2: RowStats partial sums exchanged through the XCD-local L2 (atomic publish + atomic polls) when the 4 column-tile owners of a row panel are on one XCD (XCC-id table published at kernel start); on
# speedup vs baseline: 1.0053x; 1.0026x over previous
_ZN12_GLOBAL__N_12mkENS_6ParamsE:
	s_mov_b64 s[26:27], s[0:1]
	s_load_dwordx4 s[56:59], s[0:1], 0xd8
	s_load_dwordx2 s[46:47], s[0:1], 0xe8
	s_add_u32 s0, s26, 0xe8
	s_addc_u32 s1, s27, 0
	v_and_b32_e32 v244, 0x3ff, v0
	v_writelane_b32 v254, s0, 0
	s_mov_b32 s78, s2
	v_cmp_gt_u32_e32 vcc, 16, v244
	v_writelane_b32 v254, s1, 1
	v_writelane_b32 v255, 0, 6
	s_and_saveexec_b64 s[0:1], vcc
	v_lshl_add_u32 v1, v244, 2, 0
	v_add_u32_e32 v1, 0x23fc0, v1
	v_mov_b32_e32 v2, 0
	ds_write_b32 v1, v2
	s_or_b64 exec, exec, s[0:1]
	s_waitcnt lgkmcnt(0)
	s_barrier
	s_add_u32 s0, s56, 0xf500000
	s_getreg_b32 s2, hwreg(HW_REG_XCC_ID, 0, 4)
	s_addc_u32 s1, s57, 0
	s_and_b32 s6, s2, 15
	v_cmp_eq_u32_e64 s[22:23], 0, v244
	s_and_saveexec_b64 s[2:3], s[22:23]
	s_cbranch_execz .LBB0_5
	s_mov_b64 s[4:5], exec
	v_mbcnt_lo_u32_b32 v1, s4, 0
	v_mbcnt_hi_u32_b32 v1, s5, v1
	v_cmp_eq_u32_e32 vcc, 0, v1
	s_and_b64 s[8:9], exec, vcc
	s_mov_b64 exec, s[8:9]
	s_cbranch_execz .LBB0_5
	s_lshl_b32 s7, s6, 8
	s_bcnt1_i32_b64 s4, s[4:5]
	v_mov_b32_e32 v1, s7
	v_mov_b32_e32 v2, s4
	global_atomic_add v1, v2, s[0:1] offset:1024
	s_lshl_b32 s7, s78, 2
	s_add_i32 s7, s7, 0x1ff000
	v_mov_b32_e32 v3, s7
	s_add_i32 s7, s6, 1
	v_mov_b32_e32 v4, s7
	global_store_dword v3, v4, s[0:1] sc1

.LBB0_878:
	s_nop 1
	v_mul_f32_e32 v2, v135, v135
	v_mul_f32_e32 v3, v137, v137
	v_fmac_f32_e32 v2, v134, v134
	v_fmac_f32_e32 v3, v136, v136
	v_add_f32_e32 v2, v2, v3
	v_mul_f32_e32 v3, v131, v131
	v_mul_f32_e32 v4, v133, v133
	v_fmac_f32_e32 v3, v130, v130
	v_fmac_f32_e32 v4, v132, v132
	v_add_f32_e32 v3, v3, v4
	v_add_f32_e32 v2, v3, v2
	v_mul_f32_e32 v3, v71, v71
	v_mul_f32_e32 v4, v73, v73
	v_fmac_f32_e32 v3, v70, v70
	v_fmac_f32_e32 v4, v72, v72
	v_add_f32_e32 v3, v3, v4
	v_add_f32_e32 v2, v2, v3
	v_mul_f32_e32 v3, v69, v69
	v_mul_f32_e32 v4, v67, v67
	v_fmac_f32_e32 v3, v68, v68
	v_fmac_f32_e32 v4, v66, v66
	v_add_f32_e32 v3, v3, v4
	v_add_f32_e32 v2, v3, v2
	v_mov_b32_e32 v3, v2
	s_nop 1
	v_permlane16_swap_b32_e32 v2, v3
	v_add_f32_e32 v2, v2, v3
	s_lshl_b32 s6, s45, 2
	v_mov_b32_e32 v3, v2
	v_cmp_gt_u32_e32 vcc, 16, v0
	s_add_i32 s6, s6, 0
	v_permlane32_swap_b32_e32 v2, v3
	s_and_saveexec_b64 s[10:11], vcc
	s_xor_b64 s[10:11], exec, s[10:11]
	s_lshl_b32 s7, s44, 10
	s_add_i32 s7, s6, s7
	v_add_f32_e32 v2, v2, v3
	v_lshl_add_u32 v3, v164, 4, s7
	ds_write_b32 v3, v2
	s_or_b64 exec, exec, s[10:11]
	v_mul_f32_e32 v2, v127, v127
	v_mul_f32_e32 v3, v129, v129
	v_fmac_f32_e32 v2, v126, v126
	v_fmac_f32_e32 v3, v128, v128
	v_add_f32_e32 v2, v2, v3
	v_mul_f32_e32 v3, v123, v123
	v_mul_f32_e32 v4, v125, v125
	v_fmac_f32_e32 v3, v122, v122
	v_fmac_f32_e32 v4, v124, v124
	v_add_f32_e32 v3, v3, v4
	v_add_f32_e32 v2, v3, v2
	v_mul_f32_e32 v3, v63, v63
	v_mul_f32_e32 v4, v65, v65
	v_fmac_f32_e32 v3, v62, v62
	v_fmac_f32_e32 v4, v64, v64
	v_add_f32_e32 v3, v3, v4
	v_add_f32_e32 v2, v2, v3
	v_mul_f32_e32 v3, v59, v59
	v_mul_f32_e32 v4, v61, v61
	v_fmac_f32_e32 v3, v58, v58
	v_fmac_f32_e32 v4, v60, v60
	v_add_f32_e32 v3, v3, v4
	v_add_f32_e32 v2, v3, v2
	v_mov_b32_e32 v3, v2
	s_nop 1
	v_permlane16_swap_b32_e32 v2, v3
	v_add_f32_e32 v2, v2, v3
	v_mov_b32_e32 v3, v2
	s_nop 1
	v_permlane32_swap_b32_e32 v2, v3
	s_and_saveexec_b64 s[10:11], vcc
	s_mov_b32 s45, 0x12000
	s_lshl_b32 s7, s44, 10
	s_add_i32 s7, s6, s7
	v_add_f32_e32 v2, v2, v3
	v_lshl_add_u32 v3, v164, 4, s7
	ds_write_b32 v3, v2 offset:256
	s_or_b64 exec, exec, s[10:11]
	v_mul_f32_e32 v2, v119, v119
	v_mul_f32_e32 v3, v121, v121
	v_fmac_f32_e32 v2, v118, v118
	v_fmac_f32_e32 v3, v120, v120
	v_add_f32_e32 v2, v2, v3
	v_mul_f32_e32 v3, v115, v115
	v_mul_f32_e32 v4, v117, v117
	v_fmac_f32_e32 v3, v114, v114
	v_fmac_f32_e32 v4, v116, v116
	v_add_f32_e32 v3, v3, v4
	v_add_f32_e32 v2, v3, v2
	v_mul_f32_e32 v3, v55, v55
	v_mul_f32_e32 v4, v57, v57
	v_fmac_f32_e32 v3, v54, v54
	v_fmac_f32_e32 v4, v56, v56
	v_add_f32_e32 v3, v3, v4
	v_add_f32_e32 v2, v2, v3
	v_mul_f32_e32 v3, v51, v51
	v_mul_f32_e32 v4, v53, v53
	v_fmac_f32_e32 v3, v50, v50
	v_fmac_f32_e32 v4, v52, v52
	v_add_f32_e32 v3, v3, v4
	v_add_f32_e32 v2, v3, v2
	v_mov_b32_e32 v3, v2
	s_nop 1
	v_permlane16_swap_b32_e32 v2, v3
	v_add_f32_e32 v2, v2, v3
	v_mov_b32_e32 v3, v2
	s_nop 1
	v_permlane32_swap_b32_e32 v2, v3
	s_and_saveexec_b64 s[10:11], vcc
	s_lshl_b32 s7, s44, 10
	s_add_i32 s7, s6, s7
	v_add_f32_e32 v2, v2, v3
	v_lshl_add_u32 v3, v164, 4, s7
	ds_write_b32 v3, v2 offset:512
	s_or_b64 exec, exec, s[10:11]
	v_mul_f32_e32 v2, v111, v111
	v_mul_f32_e32 v3, v113, v113
	v_fmac_f32_e32 v2, v110, v110
	v_fmac_f32_e32 v3, v112, v112
	v_add_f32_e32 v2, v2, v3
	v_mul_f32_e32 v3, v107, v107
	v_mul_f32_e32 v4, v109, v109
	v_fmac_f32_e32 v3, v106, v106
	v_fmac_f32_e32 v4, v108, v108
	v_add_f32_e32 v3, v3, v4
	v_add_f32_e32 v2, v3, v2
	v_mul_f32_e32 v3, v47, v47
	v_mul_f32_e32 v4, v49, v49
	v_fmac_f32_e32 v3, v46, v46
	v_fmac_f32_e32 v4, v48, v48
	v_add_f32_e32 v3, v3, v4
	v_add_f32_e32 v2, v2, v3
	v_mul_f32_e32 v3, v43, v43
	v_mul_f32_e32 v4, v45, v45
	v_fmac_f32_e32 v3, v42, v42
	v_fmac_f32_e32 v4, v44, v44
	v_add_f32_e32 v3, v3, v4
	v_add_f32_e32 v2, v3, v2
	v_mov_b32_e32 v3, v2
	s_nop 1
	v_permlane16_swap_b32_e32 v2, v3
	v_add_f32_e32 v2, v2, v3
	v_mov_b32_e32 v3, v2
	s_nop 1
	v_permlane32_swap_b32_e32 v2, v3
	s_and_saveexec_b64 s[10:11], vcc
	s_lshl_b32 s7, s44, 10
	s_add_i32 s7, s6, s7
	v_add_f32_e32 v2, v2, v3
	v_lshl_add_u32 v3, v164, 4, s7
	ds_write_b32 v3, v2 offset:768
	s_or_b64 exec, exec, s[10:11]
	v_mul_f32_e32 v2, v103, v103
	v_mul_f32_e32 v3, v105, v105
	v_fmac_f32_e32 v2, v102, v102
	v_fmac_f32_e32 v3, v104, v104
	v_add_f32_e32 v2, v2, v3
	v_mul_f32_e32 v3, v99, v99
	v_mul_f32_e32 v4, v101, v101
	v_fmac_f32_e32 v3, v98, v98
	v_fmac_f32_e32 v4, v100, v100
	v_add_f32_e32 v3, v3, v4
	v_add_f32_e32 v2, v3, v2
	v_mul_f32_e32 v3, v39, v39
	v_mul_f32_e32 v4, v41, v41
	v_fmac_f32_e32 v3, v38, v38
	v_fmac_f32_e32 v4, v40, v40
	v_add_f32_e32 v3, v3, v4
	v_add_f32_e32 v2, v2, v3
	v_mul_f32_e32 v3, v35, v35
	v_mul_f32_e32 v4, v37, v37
	v_fmac_f32_e32 v3, v34, v34
	v_fmac_f32_e32 v4, v36, v36
	v_add_f32_e32 v3, v3, v4
	v_add_f32_e32 v2, v3, v2
	v_mov_b32_e32 v3, v2
	s_nop 1
	v_permlane16_swap_b32_e32 v2, v3
	v_add_f32_e32 v2, v2, v3
	v_mov_b32_e32 v3, v2
	s_nop 1
	v_permlane32_swap_b32_e32 v2, v3
	s_and_saveexec_b64 s[10:11], vcc
	s_lshl_b32 s7, s44, 10
	s_add_i32 s7, s6, s7
	v_add_f32_e32 v2, v2, v3
	v_lshl_add_u32 v3, v164, 4, s7
	ds_write_b32 v3, v2 offset:2048
	s_or_b64 exec, exec, s[10:11]
	v_mul_f32_e32 v2, v95, v95
	v_mul_f32_e32 v3, v97, v97
	v_fmac_f32_e32 v2, v94, v94
	v_fmac_f32_e32 v3, v96, v96
	v_add_f32_e32 v2, v2, v3
	v_mul_f32_e32 v3, v91, v91
	v_mul_f32_e32 v4, v93, v93
	v_fmac_f32_e32 v3, v90, v90
	v_fmac_f32_e32 v4, v92, v92
	v_add_f32_e32 v3, v3, v4
	v_add_f32_e32 v2, v3, v2
	v_mul_f32_e32 v3, v31, v31
	v_mul_f32_e32 v4, v33, v33
	v_fmac_f32_e32 v3, v30, v30
	v_fmac_f32_e32 v4, v32, v32
	v_add_f32_e32 v3, v3, v4
	v_add_f32_e32 v2, v2, v3
	v_mul_f32_e32 v3, v27, v27
	v_mul_f32_e32 v4, v29, v29
	v_fmac_f32_e32 v3, v26, v26
	v_fmac_f32_e32 v4, v28, v28
	v_add_f32_e32 v3, v3, v4
	v_add_f32_e32 v2, v3, v2
	v_mov_b32_e32 v3, v2
	s_nop 1
	v_permlane16_swap_b32_e32 v2, v3
	v_add_f32_e32 v2, v2, v3
	v_mov_b32_e32 v3, v2
	s_nop 1
	v_permlane32_swap_b32_e32 v2, v3
	s_and_saveexec_b64 s[10:11], vcc
	s_lshl_b32 s7, s44, 10
	s_add_i32 s7, s6, s7
	v_add_f32_e32 v2, v2, v3
	v_lshl_add_u32 v3, v164, 4, s7
	ds_write_b32 v3, v2 offset:2304
	s_or_b64 exec, exec, s[10:11]
	v_mul_f32_e32 v2, v87, v87
	v_mul_f32_e32 v3, v89, v89
	v_fmac_f32_e32 v2, v86, v86
	v_fmac_f32_e32 v3, v88, v88
	v_add_f32_e32 v2, v2, v3
	v_mul_f32_e32 v3, v83, v83
	v_mul_f32_e32 v4, v85, v85
	v_fmac_f32_e32 v3, v82, v82
	v_fmac_f32_e32 v4, v84, v84
	v_add_f32_e32 v3, v3, v4
	v_add_f32_e32 v2, v3, v2
	v_mul_f32_e32 v3, v79, v79
	v_mul_f32_e32 v4, v77, v77
	v_fmac_f32_e32 v3, v78, v78
	v_fmac_f32_e32 v4, v76, v76
	v_add_f32_e32 v3, v3, v4
	v_add_f32_e32 v2, v2, v3
	v_mul_f32_e32 v3, v81, v81
	v_mul_f32_e32 v4, v75, v75
	v_fmac_f32_e32 v3, v80, v80
	v_fmac_f32_e32 v4, v74, v74
	v_add_f32_e32 v3, v3, v4
	v_add_f32_e32 v2, v3, v2
	v_mov_b32_e32 v3, v2
	s_nop 1
	v_permlane16_swap_b32_e32 v2, v3
	v_add_f32_e32 v2, v2, v3
	v_mov_b32_e32 v3, v2
	s_nop 1
	v_permlane32_swap_b32_e32 v2, v3
	s_and_saveexec_b64 s[10:11], vcc
	s_lshl_b32 s7, s44, 10
	s_add_i32 s7, s6, s7
	v_add_f32_e32 v2, v2, v3
	v_lshl_add_u32 v3, v164, 4, s7
	ds_write_b32 v3, v2 offset:2560
	s_or_b64 exec, exec, s[10:11]
	v_mul_f32_e32 v2, v143, v143
	v_mul_f32_e32 v3, v141, v141
	v_fmac_f32_e32 v2, v142, v142
	v_fmac_f32_e32 v3, v140, v140
	v_add_f32_e32 v2, v2, v3
	v_mul_f32_e32 v3, v145, v145
	v_mul_f32_e32 v4, v139, v139
	v_fmac_f32_e32 v3, v144, v144
	v_fmac_f32_e32 v4, v138, v138
	v_add_f32_e32 v3, v3, v4
	v_add_f32_e32 v2, v3, v2
	v_mul_f32_e32 v3, v155, v155
	v_mul_f32_e32 v4, v153, v153
	v_fmac_f32_e32 v3, v154, v154
	v_fmac_f32_e32 v4, v152, v152
	v_add_f32_e32 v3, v3, v4
	v_add_f32_e32 v2, v2, v3
	v_mul_f32_e32 v3, v157, v157
	v_mul_f32_e32 v4, v147, v147
	v_fmac_f32_e32 v3, v156, v156
	v_fmac_f32_e32 v4, v146, v146
	v_add_f32_e32 v3, v3, v4
	v_add_f32_e32 v2, v3, v2
	v_mov_b32_e32 v3, v2
	s_nop 1
	v_permlane16_swap_b32_e32 v2, v3
	v_add_f32_e32 v2, v2, v3
	v_mov_b32_e32 v3, v2
	s_nop 1
	v_permlane32_swap_b32_e32 v2, v3
	s_and_saveexec_b64 s[10:11], vcc
	s_lshl_b32 s7, s44, 10
	s_add_i32 s6, s6, s7
	v_add_f32_e32 v2, v2, v3
	v_lshl_add_u32 v3, v164, 4, s6
	ds_write_b32 v3, v2 offset:2816
	s_or_b64 exec, exec, s[10:11]
	s_waitcnt lgkmcnt(0)
	s_barrier
	v_cmp_gt_u32_e32 vcc, 32, v0
	s_and_saveexec_b64 s[34:35], vcc
	s_cbranch_execz .LBB0_903
	v_and_b32_e32 v0, 31, v163
	v_lshl_or_b32 v4, s29, 5, v0
	v_lshl_add_u32 v0, v4, 4, 0
	ds_read_b128 v[6:9], v0
	s_lshl_b64 s[6:7], s[24:25], 18
	s_add_u32 s6, s18, s6
	s_addc_u32 s7, s19, s7
	s_ashr_i32 s29, s28, 31
	s_waitcnt lgkmcnt(0)
	v_mov_b32_e32 v2, v7
	v_mov_b32_e32 v3, v8
	v_mov_b32_e32 v7, v9
	v_pk_add_f32 v[2:3], v[2:3], v[6:7]
	s_cmp_eq_u32 s28, 0
	v_add_f32_e32 v2, v2, v3
	v_max_f32_e32 v5, 0xda24260, v2
	v_add_u32_e32 v2, s70, v4
	v_ashrrev_i32_e32 v3, 31, v2
	v_lshl_add_u64 v[2:3], v[2:3], 4, s[6:7]
	s_mov_b64 s[6:7], 0xf540000
	v_lshl_add_u64 v[2:3], v[2:3], 0, s[6:7]
	v_lshl_add_u64 v[6:7], s[28:29], 2, v[2:3]
	v_readlane_b32 s12, v255, 6
	s_cmp_lg_u32 s12, 0
	s_cbranch_scc1 .Lrx_have
	s_and_b32 s12, s94, 63
	s_lshl_b32 s12, s12, 2
	s_add_i32 s12, s12, 0xf6ff000
	v_mov_b32_e32 v230, s12
	global_load_dword v228, v230, s[96:97] sc1
	global_load_dword v229, v230, s[96:97] offset:256 sc1
	global_load_dword v232, v230, s[96:97] offset:512 sc1
	global_load_dword v233, v230, s[96:97] offset:768 sc1
	s_waitcnt vmcnt(0)
	v_cmp_eq_u32_e32 vcc, v228, v229
	s_mov_b64 s[6:7], vcc
	v_cmp_eq_u32_e32 vcc, v232, v233
	s_and_b64 s[6:7], s[6:7], vcc
	v_cmp_eq_u32_e32 vcc, v228, v232
	s_and_b64 s[6:7], s[6:7], vcc
	v_cmp_ne_u32_e32 vcc, 0, v228
	s_and_b64 s[6:7], s[6:7], vcc
	s_cmp_eq_u64 s[6:7], exec
	s_cselect_b32 s12, 1, 2
	v_writelane_b32 v255, s12, 6
.Lrx_have:
	s_cmp_eq_u32 s12, 1
	s_cbranch_scc0 .Lrx_orig
	global_atomic_add v[6:7], v5, off
	s_cmp_eq_u32 s28, 0
	s_cselect_b64 s[10:11], -1, 0
	s_cmp_lg_u32 s28, 1
	s_cselect_b64 s[24:25], -1, 0
	s_cmp_lg_u32 s28, 2
	s_cselect_b64 s[38:39], -1, 0
	s_cmp_lg_u32 s28, 3
	s_cselect_b64 s[40:41], -1, 0
	v_mov_b32_e32 v230, 0
	v_mov_b32_e32 v231, 0
	s_mov_b32 s12, 0
.Lrx_loop:
	global_atomic_add_x2 v[228:229], v[2:3], v[230:231], off sc0
	global_atomic_add_x2 v[232:233], v[2:3], v[230:231], off offset:8 sc0
	s_waitcnt vmcnt(0)
	v_cmp_eq_u32_e32 vcc, 0, v228
	s_andn2_b64 s[6:7], vcc, s[10:11]
	v_cmp_eq_u32_e32 vcc, 0, v229
	s_and_b64 s[42:43], vcc, s[24:25]
	s_or_b64 s[6:7], s[6:7], s[42:43]
	v_cmp_eq_u32_e32 vcc, 0, v232
	s_and_b64 s[42:43], vcc, s[38:39]
	s_or_b64 s[6:7], s[6:7], s[42:43]
	v_cmp_eq_u32_e32 vcc, 0, v233
	s_and_b64 s[42:43], vcc, s[40:41]
	s_or_b64 s[6:7], s[6:7], s[42:43]
	s_cmp_eq_u64 s[6:7], 0
	s_cbranch_scc1 .Lrx_done
	s_add_i32 s12, s12, 1
	s_cmp_lt_u32 s12, 0x8000
	s_cbranch_scc0 .Lrx_done
	s_sleep 1
	s_branch .Lrx_loop
.Lrx_done:
	v_mov_b32_e32 v9, v228
	v_mov_b32_e32 v6, v229
	v_mov_b32_e32 v8, v232
	v_mov_b32_e32 v7, v233
	s_branch .LBB0_902
.Lrx_orig:
	s_cmp_eq_u32 s28, 0
	global_store_dword v[6:7], v5, off sc1
	s_memrealtime s[12:13]
	s_cselect_b64 s[10:11], -1, 0
	s_cmp_lg_u32 s28, 1
	s_cselect_b64 s[24:25], -1, 0
	s_cmp_lg_u32 s28, 2
	s_cselect_b64 s[38:39], -1, 0
	s_cmp_lg_u32 s28, 3
	s_cselect_b64 s[40:41], -1, 0
	s_branch .LBB0_897
